# softmax scale constants from SGPRs instead of per-instruction literals in cross-attention, SWA and MoBA own-block loops
# baseline (speedup 1.0000x reference)
; #define INP(k) ((const float*)(const GASP float*)ldptr(PT, (k)))
; #define WSP(T, off) ((T*)(GASP T*)(ldptr(PT, 26) + (off)))
; __global__ void __launch_bounds__(NT, 2) trunk_fwd(Args args) {
;     ...
;             } else {
;                 for (int u = bx; u < 1024; u += G) { const int rem = u % 8, b = rem / 2, hkv = rem % 2, qb = u / 8;
;     ...
;                     swa_unit(lds, WSP(bf16, WS_QKV), WSP(bf16, WS_AO), INP(2), INP(12) + li * 16, b, hkv, qb);
;     ...
;                     __syncthreads(); }
.Lprio_mix_done:
	s_mov_b32 s32, 0x3e38aa3b
	s_andn2_b64 vcc, exec, s[8:9]
	s_mov_b64 s[0:1], -1
	v_readlane_b32 s37, v255, 15
	v_readlane_b32 s43, v255, 20
	s_cbranch_vccnz .LBB0_547
	v_readlane_b32 s0, v254, 6
	v_readlane_b32 s1, v254, 7
	s_andn2_b64 vcc, exec, s[0:1]
	v_readlane_b32 s27, v255, 16
	v_readlane_b32 s28, v255, 17
	v_readlane_b32 s38, v255, 18
	s_cbranch_vccnz .LBB0_546
	s_lshl_b32 s86, s89, 4
	s_lshl_b64 s[0:1], s[86:87], 2
	s_mov_b32 s10, s2
	s_branch .LBB0_527

; __device__ __forceinline__ float pair_max(float v) { auto r = __builtin_amdgcn_permlane32_swap(__float_as_uint(v), __float_as_uint(v), false, false); return fmaxf(__uint_as_float(r[0]), __uint_as_float(r[1])); }
; #define LDS_FENCE() asm volatile("" ::: "memory")
; template <int NS, int DT> __device__ __forceinline__ void softmax_upd(f32x16* s, float& m, float& l, f32x16* o) {
;     float mx = s[0][0];
; #pragma unroll
;     for (int i = 0; i < NS; ++i)
; #pragma unroll
;         for (int r = 0; r < 16; ++r) mx = fmaxf(mx, s[i][r]);
;     mx = pair_max(mx);
;     const bool grow = mx > m + 8.0f; const float mn = grow ? mx : m; float sum = 0.f;
;     if (__any(grow)) { const float alpha = __builtin_amdgcn_exp2f(m - mn); l *= alpha;
; #pragma unroll
;         for (int dt = 0; dt < DT; ++dt) o[dt] = o[dt] * alpha; }
; __device__ __forceinline__ void swa_unit(lbyte* lds, const bf16* QKV, bf16* AO, const float* rel_bias, const float* sinks, int b, int hkv, int qb) {
;     ...
;         for (int j = 0; j < 6; ++j) { const int ks = k0 + 32 * j;
;             if (ks > qs + 31 || ks + 31 < qs - 127 || ks + 31 < 0) continue;
;             f32x16 s[1]; s16x8 kf[4], vf[4]; load_k<4>(kf, lds + SW_K + 32 * j * KP64, KP64, l31, h); load_v<2>(vf, lds + SW_V + 64 * j, SW_VP, l31, h); LDS_FENCE(); qk1<4>(s[0], kf, qf);
; #pragma unroll
;             for (int r = 0; r < 16; ++r) { const int key = ks + kkrow(r, h), dist = tq - key; const float bias = bt[wid * 320 + dist + 64]; s[0][r] = key >= 0 ? s[0][r] * (0.125f * LOG2E) + bias : -INFINITY; }
;             softmax_upd<1, 2>(s, m, l, o);
.LBB0_542:
	s_cmp_gt_i32 s12, s8
	s_cbranch_scc1 .LBB0_541
	s_add_i32 s15, s12, 31
	s_cmp_lt_i32 s15, s9
	s_cselect_b64 s[16:17], -1, 0
	s_cmp_lt_i32 s12, 0
	s_cselect_b64 s[20:21], -1, 0
	s_or_b64 s[16:17], s[20:21], s[16:17]
	s_and_b64 vcc, exec, s[16:17]
	s_cbranch_vccnz .LBB0_541
	ds_read_b128 v[34:37], v102
	ds_read_b128 v[88:91], v102 offset:32
	ds_read_b128 v[92:95], v102 offset:64
	ds_read_b128 v[104:107], v102 offset:96
	v_add_u32_e32 v38, s13, v98
	ds_read2_b64 v[78:81], v38 offset1:2
	ds_read2_b64 v[70:73], v38 offset0:4 offset1:6
	v_add_u32_e32 v38, 0x3000, v38
	ds_read2_b64 v[74:77], v38 offset0:64 offset1:66
	ds_read2_b64 v[66:69], v38 offset0:68 offset1:70
	s_waitcnt vmcnt(3) lgkmcnt(7)
	v_mfma_f32_32x32x16_bf16 v[34:49], v[34:37], v[50:53], 0
	s_waitcnt vmcnt(2) lgkmcnt(6)
	v_mfma_f32_32x32x16_bf16 v[34:49], v[88:91], v[54:57], v[34:49]
	ds_read2_b32 v[90:91], v101 offset0:18 offset1:19
	ds_read2_b32 v[88:89], v101 offset0:16 offset1:17
	s_waitcnt vmcnt(1) lgkmcnt(7)
	v_mfma_f32_32x32x16_bf16 v[34:49], v[92:95], v[58:61], v[34:49]
	ds_read2_b32 v[94:95], v101 offset0:26 offset1:27
	ds_read2_b32 v[92:93], v101 offset0:24 offset1:25
	s_waitcnt vmcnt(0) lgkmcnt(8)
	v_mfma_f32_32x32x16_bf16 v[34:49], v[104:107], v[62:65], v[34:49]
	s_waitcnt lgkmcnt(2)
	s_nop 10
	v_fmac_f32_e32 v89, s32, v40
	v_fmac_f32_e32 v88, s32, v41
	ds_read2_b32 v[40:41], v101 offset0:10 offset1:11
	s_waitcnt lgkmcnt(2)
	v_fmac_f32_e32 v95, s32, v34
	v_fmac_f32_e32 v94, s32, v35
	v_fmac_f32_e32 v91, s32, v38
	v_fmac_f32_e32 v90, s32, v39
	ds_read2_b32 v[38:39], v101 offset0:8 offset1:9
	ds_read2_b32 v[34:35], v101 offset1:1
	s_waitcnt lgkmcnt(3)
	v_fmac_f32_e32 v93, s32, v36
	v_fmac_f32_e32 v92, s32, v37
	s_waitcnt lgkmcnt(2)
	v_fmac_f32_e32 v41, s32, v42
	ds_read2_b32 v[36:37], v101 offset0:2 offset1:3
	v_max_f32_e32 v42, v95, v94
	v_max3_f32 v42, v42, v93, v92
	v_max3_f32 v42, v42, v91, v90
	v_fmac_f32_e32 v40, s32, v43
	v_max3_f32 v42, v42, v89, v88
	s_waitcnt lgkmcnt(2)
	v_fmac_f32_e32 v39, s32, v44
	v_fmac_f32_e32 v38, s32, v45
	v_max3_f32 v42, v42, v41, v40
	s_waitcnt lgkmcnt(0)
	v_fmac_f32_e32 v37, s32, v46
	v_fmac_f32_e32 v36, s32, v47
	v_max3_f32 v42, v42, v39, v38
	v_fmac_f32_e32 v35, s32, v48
	v_fmac_f32_e32 v34, s32, v49
	v_max3_f32 v42, v42, v37, v36
	v_max3_f32 v42, v42, v35, v34
	v_mov_b32_e32 v43, v42
	s_nop 1
	v_permlane32_swap_b32_e32 v42, v43
	v_max_f32_e32 v43, v43, v43
	v_max_f32_e32 v42, v42, v42
	v_max_f32_e32 v42, v42, v43
	v_add_f32_e32 v43, 0x41000000, v103
	v_cmp_gt_f32_e32 vcc, v42, v43
	s_nop 1
	v_cndmask_b32_e32 v42, v103, v42, vcc
	s_cbranch_vccz .LBB0_540
	v_sub_f32_e32 v43, v103, v42
	v_exp_f32_e32 v44, v43
	s_nop 0
	v_mul_f32_e32 v100, v100, v44
	v_pk_mul_f32 v[16:17], v[16:17], v[44:45] op_sel_hi:[1,0]
	v_pk_mul_f32 v[14:15], v[14:15], v[44:45] op_sel_hi:[1,0]
	v_pk_mul_f32 v[12:13], v[12:13], v[44:45] op_sel_hi:[1,0]
	v_pk_mul_f32 v[10:11], v[10:11], v[44:45] op_sel_hi:[1,0]
	v_pk_mul_f32 v[8:9], v[8:9], v[44:45] op_sel_hi:[1,0]
	v_pk_mul_f32 v[6:7], v[6:7], v[44:45] op_sel_hi:[1,0]
	v_pk_mul_f32 v[4:5], v[4:5], v[44:45] op_sel_hi:[1,0]
	v_pk_mul_f32 v[2:3], v[2:3], v[44:45] op_sel_hi:[1,0]
	v_pk_mul_f32 v[32:33], v[32:33], v[44:45] op_sel_hi:[1,0]
	v_pk_mul_f32 v[30:31], v[30:31], v[44:45] op_sel_hi:[1,0]
	v_pk_mul_f32 v[28:29], v[28:29], v[44:45] op_sel_hi:[1,0]
	v_pk_mul_f32 v[26:27], v[26:27], v[44:45] op_sel_hi:[1,0]
	v_pk_mul_f32 v[24:25], v[24:25], v[44:45] op_sel_hi:[1,0]
	v_pk_mul_f32 v[22:23], v[22:23], v[44:45] op_sel_hi:[1,0]
	v_pk_mul_f32 v[20:21], v[20:21], v[44:45] op_sel_hi:[1,0]
	v_pk_mul_f32 v[18:19], v[18:19], v[44:45] op_sel_hi:[1,0]
	s_branch .LBB0_540

; #define LDS_FENCE() asm volatile("" ::: "memory")
; template <bool CAUSAL> __device__ __forceinline__ void moba_span(lbyte* kbuf, lbyte* vbuf, const bf16* Kh, const bf16* Vh, int kpos0, int nsub, const s16x8* qf, int tq, bool valid, int qlo, int qhi, ...
;     ...
;         const int key0 = kpos0 + 32 * su;
;         sub_write(st, kbuf, vbuf, lane);
;         if (su + 1 < nsub) sub_load(st, Kh + (size_t)(key0 + 32) * 64, Vh + (size_t)(key0 + 32) * 64, lane);
;         s16x8 kf[4], vf[4]; f32x16 s[1];
;         load_k<4>(kf, kbuf, KP64, l31, h); load_v_tr<2>(vf, vbuf, lane); LDS_FENCE();
;         qk1<4>(s[0], kf, qf);
;         const int dmin = qlo - (key0 + 31), dmax = qhi - key0;
;         const int bmin = t5_bucket(dmin > 0 ? dmin : 0), bmax = t5_bucket(dmax > 0 ? dmax : 0);
;         if (!CAUSAL && bmax - bmin <= 1) {
;             const float t0 = tab[bmin], t1 = tab[bmax]; const int th1 = thr[bmax];
;             float mxr = s[0][0];
; #pragma unroll
;             for (int r = 1; r < 16; ++r) mxr = fmaxf(mxr, s[0][r]);
;             mxr = pair_max(mxr);
;             const float cL = valid ? 0.125f * LOG2E : 0.f, bL = valid ? t0 : -INFINITY, mx = valid ? mxr * (0.125f * LOG2E) + fmaxf(t0, t1) : -INFINITY;
;             const bool grow = mx > m + 8.0f; const float mn = grow ? mx : m, off = bL - mn, offB = off + (t1 - t0);
;             if (__any(grow)) { const float alpha = __builtin_amdgcn_exp2f(m - mn); l *= alpha; o[0] = o[0] * alpha; o[1] = o[1] * alpha; }
;             m = mn;
;             const int x1 = (bmax > bmin) ? tq - key0 - th1 : -0x40000000; f32x2_t sum2 = {0.f, 0.f};
; #pragma unroll
;             for (int r = 0; r < 16; r += 2) { const int kk = kkrow(r, h);
;                 const f32x2_t ob = {x1 >= kk ? offB : off, x1 >= kk + 1 ? offB : off}; f32x2_t v = {s[0][r], s[0][r + 1]}; v = v * (f32x2_t){cL, cL} + ob;
;                 const float e0 = __builtin_amdgcn_exp2f(v.x), e1 = __builtin_amdgcn_exp2f(v.y); s[0][r] = e0; s[0][r + 1] = e1; sum2 += (f32x2_t){e0, e1}; }
;             l += pair_sum(sum2.x + sum2.y);
;         } else {
;             float bb[16];
; #pragma unroll
;             for (int r = 0; r < 16; ++r) { int dist = tq - (key0 + kkrow(r, h)); dist = dist > 0 ? dist : 0; bb[r] = dtab[dist < MC_NDT - 1 ? dist : MC_NDT - 1]; }
;             LDS_FENCE();
; #pragma unroll
.LBB0_648:
	v_med3_i32 v38, v126, 0, v239
	v_add_u32_e32 v39, -1, v126
	v_add_u32_e32 v40, -2, v126
	v_add_u32_e32 v41, -3, v126
	v_add_u32_e32 v42, -8, v126
	v_add_u32_e32 v43, -9, v126
	v_add_u32_e32 v44, -10, v126
	v_add_u32_e32 v45, -11, v126
	ds_read_b128 v[34:37], v129 offset:36864
	ds_read_b128 v[132:135], v129 offset:36896
	ds_read_b128 v[136:139], v129 offset:36928
	ds_read_b128 v[140:143], v129 offset:36960
	ds_read_b64_tr_b16 v[110:111], v130 offset:41472
	ds_read_b64_tr_b16 v[112:113], v130 offset:42048
	ds_read_b64_tr_b16 v[108:109], v130 offset:42112
	ds_read_b64_tr_b16 v[106:107], v130 offset:41536
	ds_read_b64_tr_b16 v[102:103], v130 offset:43776
	ds_read_b64_tr_b16 v[104:105], v130 offset:44352
	ds_read_b64_tr_b16 v[100:101], v130 offset:44416
	ds_read_b64_tr_b16 v[98:99], v130 offset:43840
	v_lshl_add_u32 v38, v38, 2, s82
	v_med3_i32 v39, v39, 0, v239
	v_med3_i32 v40, v40, 0, v239
	v_med3_i32 v41, v41, 0, v239
	v_med3_i32 v42, v42, 0, v239
	v_med3_i32 v43, v43, 0, v239
	v_med3_i32 v44, v44, 0, v239
	v_med3_i32 v45, v45, 0, v239
	v_lshl_add_u32 v39, v39, 2, s82
	v_lshl_add_u32 v40, v40, 2, s82
	v_lshl_add_u32 v41, v41, 2, s82
	v_lshl_add_u32 v42, v42, 2, s82
	v_lshl_add_u32 v43, v43, 2, s82
	v_lshl_add_u32 v44, v44, 2, s82
	v_lshl_add_u32 v45, v45, 2, s82
	ds_read_b32 v114, v38
	ds_read_b32 v144, v39
	ds_read_b32 v145, v40
	ds_read_b32 v146, v41
	ds_read_b32 v147, v42
	ds_read_b32 v148, v43
	ds_read_b32 v149, v44
	ds_read_b32 v150, v45
	v_add_u32_e32 v38, -16, v126
	v_med3_i32 v38, v38, 0, v239
	v_lshl_add_u32 v151, v38, 2, s82
	v_subrev_u32_e32 v38, 17, v126
	v_med3_i32 v38, v38, 0, v239
	v_lshl_add_u32 v152, v38, 2, s82
	v_subrev_u32_e32 v38, 18, v126
	v_med3_i32 v38, v38, 0, v239
	v_lshl_add_u32 v153, v38, 2, s82
	s_waitcnt lgkmcnt(14)
	v_mfma_f32_32x32x16_bf16 v[34:49], v[34:37], v[62:65], 0
	v_subrev_u32_e32 v154, 19, v126
	v_subrev_u32_e32 v155, 24, v126
	v_subrev_u32_e32 v156, 25, v126
	v_med3_i32 v154, v154, 0, v239
	v_med3_i32 v155, v155, 0, v239
	v_med3_i32 v156, v156, 0, v239
	v_lshl_add_u32 v154, v154, 2, s82
	v_mfma_f32_32x32x16_bf16 v[34:49], v[132:135], v[66:69], v[34:49]
	v_subrev_u32_e32 v133, 26, v126
	v_med3_i32 v133, v133, 0, v239
	v_subrev_u32_e32 v134, 27, v126
	v_lshl_add_u32 v133, v133, 2, s82
	v_med3_i32 v134, v134, 0, v239
	v_lshl_add_u32 v155, v155, 2, s82
	v_lshl_add_u32 v132, v156, 2, s82
	v_mfma_f32_32x32x16_bf16 v[34:49], v[136:139], v[54:57], v[34:49]
	v_lshl_add_u32 v134, v134, 2, s82
	ds_read_b32 v135, v151
	ds_read_b32 v136, v152
	ds_read_b32 v137, v153
	ds_read_b32 v138, v154
	ds_read_b32 v139, v155
	ds_read_b32 v151, v132
	ds_read_b32 v152, v133
	ds_read_b32 v153, v134
	v_subrev_u32_e32 v133, 27, v127
	v_cmp_ge_i32_e32 vcc, v182, v133
	v_mfma_f32_32x32x16_bf16 v[34:49], v[140:143], v[50:53], v[34:49]
	s_waitcnt lgkmcnt(14)
	s_nop 10
	v_fmac_f32_e32 v114, s32, v34
	v_cndmask_b32_e32 v132, v238, v114, vcc
	v_fmac_f32_e32 v144, s32, v35
	v_cmp_gt_i32_e32 vcc, v182, v133
	v_subrev_u32_e32 v34, 25, v127
	s_waitcnt lgkmcnt(13)
	v_fmac_f32_e32 v145, s32, v36
	v_cndmask_b32_e32 v133, v238, v144, vcc
	v_cmp_ge_i32_e32 vcc, v182, v34
	v_subrev_u32_e32 v34, 24, v127
	s_waitcnt lgkmcnt(12)
	v_fmac_f32_e32 v146, s32, v37
	v_cndmask_b32_e32 v36, v238, v145, vcc
	v_cmp_ge_i32_e32 vcc, v182, v34
	v_subrev_u32_e32 v34, 19, v127
	s_waitcnt lgkmcnt(11)
	v_fmac_f32_e32 v147, s32, v38
	v_cndmask_b32_e32 v134, v238, v146, vcc
	v_cmp_ge_i32_e32 vcc, v182, v34
	v_subrev_u32_e32 v34, 18, v127
	s_waitcnt lgkmcnt(10)
	v_fmac_f32_e32 v148, s32, v39
	v_cndmask_b32_e32 v37, v238, v147, vcc
	v_cmp_ge_i32_e32 vcc, v182, v34
	v_subrev_u32_e32 v34, 17, v127
	s_waitcnt lgkmcnt(9)
	v_fmac_f32_e32 v149, s32, v40
	v_cndmask_b32_e32 v38, v238, v148, vcc
	v_cmp_ge_i32_e32 vcc, v182, v34
	v_add_u32_e32 v34, -16, v127
	s_waitcnt lgkmcnt(8)
	v_fmac_f32_e32 v150, s32, v41
	v_cndmask_b32_e32 v39, v238, v149, vcc
	v_cmp_ge_i32_e32 vcc, v182, v34
	v_add_u32_e32 v34, -11, v127
	s_waitcnt lgkmcnt(7)
	v_fmac_f32_e32 v135, s32, v42
	v_cndmask_b32_e32 v41, v238, v150, vcc
	v_cmp_ge_i32_e32 vcc, v182, v34
	v_add_u32_e32 v34, -10, v127
	s_waitcnt lgkmcnt(6)
	v_fmac_f32_e32 v136, s32, v43
	v_cndmask_b32_e32 v40, v238, v135, vcc
	v_cmp_ge_i32_e32 vcc, v182, v34
	v_add_u32_e32 v34, -9, v127
	s_waitcnt lgkmcnt(5)
	v_fmac_f32_e32 v137, s32, v44
	v_cndmask_b32_e32 v42, v238, v136, vcc
	v_cmp_ge_i32_e32 vcc, v182, v34
	v_add_u32_e32 v34, -8, v127
	s_waitcnt lgkmcnt(2)
	v_fmac_f32_e32 v151, s32, v47
	v_max_f32_e32 v47, v132, v133
	v_cndmask_b32_e32 v43, v238, v137, vcc
	v_fmac_f32_e32 v138, s32, v45
	v_cmp_ge_i32_e32 vcc, v182, v34
	v_add_u32_e32 v34, -3, v127
	v_max3_f32 v47, v47, v36, v134
	v_cndmask_b32_e32 v45, v238, v138, vcc
	v_fmac_f32_e32 v139, s32, v46
	v_cmp_ge_i32_e32 vcc, v182, v34
	v_add_u32_e32 v34, -2, v127
	v_max3_f32 v47, v47, v37, v38
	v_cndmask_b32_e32 v44, v238, v139, vcc
	v_cmp_ge_i32_e32 vcc, v182, v34
	v_add_u32_e32 v34, -1, v127
	v_max3_f32 v47, v47, v39, v41
	v_cndmask_b32_e32 v46, v238, v151, vcc
	s_waitcnt lgkmcnt(1)
	v_fmac_f32_e32 v152, s32, v48
	v_cmp_ge_i32_e32 vcc, v182, v34
	v_max3_f32 v47, v47, v40, v42
	s_waitcnt lgkmcnt(0)
	v_fmac_f32_e32 v153, s32, v49
	v_cndmask_b32_e32 v34, v238, v152, vcc
	v_cmp_ge_i32_e32 vcc, v182, v127
	v_max3_f32 v47, v47, v43, v45
	v_max3_f32 v47, v47, v44, v46
	v_cndmask_b32_e32 v35, v238, v153, vcc
	v_max3_f32 v47, v47, v34, v35
	v_mov_b32_e32 v48, v47
	s_nop 1
	v_permlane32_swap_b32_e32 v47, v48
	v_max_f32_e32 v48, v48, v48
	v_max_f32_e32 v47, v47, v47
	v_max_f32_e32 v47, v47, v48
	v_add_f32_e32 v48, 0x41000000, v131
	v_cmp_gt_f32_e32 vcc, v47, v48
	s_nop 1
	v_cndmask_b32_e32 v114, v131, v47, vcc
	s_cbranch_vccz .LBB0_650
	v_sub_f32_e32 v47, v131, v114
	v_exp_f32_e32 v48, v47
	s_nop 0
	v_mul_f32_e32 v115, v115, v48
	v_pk_mul_f32 v[32:33], v[32:33], v[48:49] op_sel_hi:[1,0]
	v_pk_mul_f32 v[30:31], v[30:31], v[48:49] op_sel_hi:[1,0]
	v_pk_mul_f32 v[28:29], v[28:29], v[48:49] op_sel_hi:[1,0]
	v_pk_mul_f32 v[26:27], v[26:27], v[48:49] op_sel_hi:[1,0]
	v_pk_mul_f32 v[24:25], v[24:25], v[48:49] op_sel_hi:[1,0]
	v_pk_mul_f32 v[22:23], v[22:23], v[48:49] op_sel_hi:[1,0]
	v_pk_mul_f32 v[20:21], v[20:21], v[48:49] op_sel_hi:[1,0]
	v_pk_mul_f32 v[18:19], v[18:19], v[48:49] op_sel_hi:[1,0]
	v_pk_mul_f32 v[16:17], v[16:17], v[48:49] op_sel_hi:[1,0]
	v_pk_mul_f32 v[14:15], v[14:15], v[48:49] op_sel_hi:[1,0]
	v_pk_mul_f32 v[12:13], v[12:13], v[48:49] op_sel_hi:[1,0]
	v_pk_mul_f32 v[10:11], v[10:11], v[48:49] op_sel_hi:[1,0]
	v_pk_mul_f32 v[8:9], v[8:9], v[48:49] op_sel_hi:[1,0]
	v_pk_mul_f32 v[6:7], v[6:7], v[48:49] op_sel_hi:[1,0]
	v_pk_mul_f32 v[4:5], v[4:5], v[48:49] op_sel_hi:[1,0]
	v_pk_mul_f32 v[2:3], v[2:3], v[48:49] op_sel_hi:[1,0]

; __device__ __forceinline__ float pair_max(float v) { auto r = __builtin_amdgcn_permlane32_swap(__float_as_uint(v), __float_as_uint(v), false, false); return fmaxf(__uint_as_float(r[0]), __uint_as_float(r[1])); }
; template <bool CAUSAL> __device__ __forceinline__ void moba_span(lbyte* kbuf, lbyte* vbuf, const bf16* Kh, const bf16* Vh, int kpos0, int nsub, const s16x8* qf, int tq, bool valid, int qlo, int qhi, ...
;     ...
;         if (!CAUSAL && bmax - bmin <= 1) {
;             const float t0 = tab[bmin], t1 = tab[bmax]; const int th1 = thr[bmax];
;             float mxr = s[0][0];
; #pragma unroll
;             for (int r = 1; r < 16; ++r) mxr = fmaxf(mxr, s[0][r]);
;             mxr = pair_max(mxr);
;             const float cL = valid ? 0.125f * LOG2E : 0.f, bL = valid ? t0 : -INFINITY, mx = valid ? mxr * (0.125f * LOG2E) + fmaxf(t0, t1) : -INFINITY;
;             const bool grow = mx > m + 8.0f; const float mn = grow ? mx : m, off = bL - mn, offB = off + (t1 - t0);
;             if (__any(grow)) { const float alpha = __builtin_amdgcn_exp2f(m - mn); l *= alpha; o[0] = o[0] * alpha; o[1] = o[1] * alpha; }
;             m = mn;
.LBB0_671:
	s_and_b64 vcc, exec, s[24:25]
	s_cbranch_vccz .LBB0_675
	s_lshl_b32 s21, s15, 2
	s_add_i32 s23, 0, 0x23f50
	s_add_i32 s21, s23, s21
	v_mov_b32_e32 v34, s21
	s_lshl_b32 s21, s17, 2
	s_add_i32 s23, s23, s21
	s_add_i32 s21, s21, 0
	s_add_i32 s21, s21, 0x23fd0
	v_mov_b32_e32 v36, s23
	v_mov_b32_e32 v37, s21
	ds_read_b32 v35, v34
	ds_read_b32 v36, v36
	ds_read_b32 v34, v37
	v_max_f32_e32 v37, v66, v67
	v_max3_f32 v37, v37, v68, v69
	v_max3_f32 v37, v37, v70, v71
	v_max3_f32 v37, v37, v72, v73
	v_max3_f32 v37, v37, v74, v75
	v_max3_f32 v37, v37, v76, v77
	v_max3_f32 v37, v37, v78, v79
	v_max3_f32 v37, v37, v80, v81
	v_mov_b32_e32 v38, v37
	s_nop 1
	v_permlane32_swap_b32_e32 v37, v38
	v_max_f32_e32 v37, v37, v38
	s_waitcnt lgkmcnt(1)
	v_max_f32_e32 v38, v35, v36
	v_fmac_f32_e32 v38, s32, v37
	v_cndmask_b32_e64 v37, v238, v38, s[8:9]
	v_cmp_gt_f32_e32 vcc, v37, v0
	s_nop 1
	v_cndmask_b32_e32 v194, v231, v37, vcc
	s_cbranch_vccz .LBB0_674
	v_sub_f32_e32 v0, v231, v194
	v_exp_f32_e32 v0, v0
	s_nop 0
	v_mul_f32_e32 v195, v195, v0
	v_pk_mul_f32 v[32:33], v[32:33], v[0:1] op_sel_hi:[1,0]
	v_pk_mul_f32 v[30:31], v[30:31], v[0:1] op_sel_hi:[1,0]
	v_pk_mul_f32 v[28:29], v[28:29], v[0:1] op_sel_hi:[1,0]
	v_pk_mul_f32 v[26:27], v[26:27], v[0:1] op_sel_hi:[1,0]
	v_pk_mul_f32 v[24:25], v[24:25], v[0:1] op_sel_hi:[1,0]
	v_pk_mul_f32 v[22:23], v[22:23], v[0:1] op_sel_hi:[1,0]
	v_pk_mul_f32 v[20:21], v[20:21], v[0:1] op_sel_hi:[1,0]
	v_pk_mul_f32 v[16:17], v[16:17], v[0:1] op_sel_hi:[1,0]
	v_pk_mul_f32 v[14:15], v[14:15], v[0:1] op_sel_hi:[1,0]
	v_pk_mul_f32 v[12:13], v[12:13], v[0:1] op_sel_hi:[1,0]
	v_pk_mul_f32 v[10:11], v[10:11], v[0:1] op_sel_hi:[1,0]
	v_pk_mul_f32 v[8:9], v[8:9], v[0:1] op_sel_hi:[1,0]
	v_pk_mul_f32 v[6:7], v[6:7], v[0:1] op_sel_hi:[1,0]
	v_pk_mul_f32 v[4:5], v[4:5], v[0:1] op_sel_hi:[1,0]
	v_pk_mul_f32 v[18:19], v[18:19], v[0:1] op_sel_hi:[1,0]
	v_pk_mul_f32 v[2:3], v[2:3], v[0:1] op_sel_hi:[1,0]

; __device__ __forceinline__ unsigned pk2(float lo, float hi) { f32x2_t v = {lo, hi}; bf16x2_t b = __builtin_convertvector(v, bf16x2_t); return __builtin_bit_cast(unsigned, b); }
; __device__ __forceinline__ float pair_sum(float v) { auto r = __builtin_amdgcn_permlane32_swap(__float_as_uint(v), __float_as_uint(v), false, false); return __uint_as_float(r[0]) + __uint_as_float(r[1]); }
; __device__ __forceinline__ void cross_unit(lbyte* lds, bf16* CQ, const bf16* CKV, const float* gq, const float* gk, int layer, int b, int hc, int qblk0, int qstep, int nq) {
;     ...
;     for (int qi = 0; qi < nq; ++qi) { const int qblk = qblk0 + qi * qstep;
;     const size_t row = (size_t)b * SEQ + qblk * 256 + 32 * wid + l31;
;     bf16* qrow = CQ + row * 512 + hc * 128;
;     s16x8 qf[8];
; #pragma unroll
;     for (int c = 0; c < 8; ++c) qf[c] = *(const s16x8*)(qrow + 16 * c + 8 * h);
;     { float ss = 0.f;
; #pragma unroll
;       for (int c = 0; c < 8; ++c)
; #pragma unroll
;           for (int e2 = 0; e2 < 8; ++e2) { const float f = bf2f((unsigned short)qf[c][e2]); ss += f * f; }
;       ss = pair_sum(ss); const float rn = __builtin_amdgcn_rsqf(ss * (1.0f / 128.0f) + 1e-6f);
; #pragma unroll
;       for (int c = 0; c < 8; ++c) { const f32x4 ga = *(const f32x4*)(gq + 16 * c + 8 * h), gb = *(const f32x4*)(gq + 16 * c + 8 * h + 4); u32x4 w;
;           w.x = pk2(bf2f((unsigned short)qf[c][0]) * rn * ga[0], bf2f((unsigned short)qf[c][1]) * rn * ga[1]); w.y = pk2(bf2f((unsigned short)qf[c][2]) * rn * ga[2], bf2f((unsigned short)qf[c][3]) * rn * ga[3]);
;           w.z = pk2(bf2f((unsigned short)qf[c][4]) * rn * gb[0], bf2f((unsigned short)qf[c][5]) * rn * gb[1]); w.w = pk2(bf2f((unsigned short)qf[c][6]) * rn * gb[2], bf2f((unsigned short)qf[c][7]) * rn * gb[3]);
;           qf[c] = __builtin_bit_cast(s16x8, w); } }
.LBB0_988:
	s_mov_b32 s12, 0x3e0293ee
	v_readlane_b32 s1, v254, 63
	s_mul_i32 s1, s0, s1
	s_add_i32 s1, s1, s68
	s_lshl_b32 s4, s1, 8
	s_ashr_i32 s5, s4, 31
	v_lshl_add_u64 v[2:3], v[148:149], 0, s[4:5]
	v_lshlrev_b64 v[2:3], 10, v[2:3]
	v_lshl_add_u64 v[154:155], v[152:153], 0, v[2:3]
	global_load_dwordx4 v[50:53], v[150:151], off offset:16
	global_load_dwordx4 v[54:57], v[150:151], off
	global_load_dwordx4 v[42:45], v[150:151], off offset:80
	global_load_dwordx4 v[46:49], v[150:151], off offset:64
	global_load_dwordx4 v[34:37], v[150:151], off offset:144
	global_load_dwordx4 v[38:41], v[150:151], off offset:128
	global_load_dwordx4 v[26:29], v[150:151], off offset:208
	global_load_dwordx4 v[30:33], v[150:151], off offset:192
	global_load_dwordx4 v[18:21], v[150:151], off offset:272
	global_load_dwordx4 v[22:25], v[150:151], off offset:256
	global_load_dwordx4 v[10:13], v[150:151], off offset:336
	global_load_dwordx4 v[14:17], v[150:151], off offset:320
	global_load_dwordx4 v[2:5], v[150:151], off offset:400
	global_load_dwordx4 v[6:9], v[150:151], off offset:384
	global_load_dwordx4 v[126:129], v[150:151], off offset:464
	global_load_dwordx4 v[130:133], v[150:151], off offset:448
	s_mov_b32 s1, 8
	v_mov_b32_e32 v158, 0
	v_mov_b32_e32 v162, 0xf149f2ca
	v_mov_b32_e32 v159, v157
	v_mov_b32_e32 v160, v156
	s_waitcnt vmcnt(23)
	v_and_b32_e32 v59, 0xffff0000, v199
	v_lshlrev_b32_e32 v58, 16, v199
	v_and_b32_e32 v61, 0xffff0000, v198
	v_lshlrev_b32_e32 v60, 16, v198
	s_waitcnt vmcnt(19)
	v_and_b32_e32 v95, 0xffff0000, v213
	v_lshlrev_b32_e32 v94, 16, v213
	v_and_b32_e32 v113, 0xffff0000, v212
	s_waitcnt vmcnt(16)
	v_and_b32_e32 v97, 0xffff0000, v224
	v_lshlrev_b32_e32 v112, 16, v212
	v_lshlrev_b32_e32 v96, 16, v224
	v_and_b32_e32 v67, 0xffff0000, v203
	v_lshlrev_b32_e32 v66, 16, v203
	v_and_b32_e32 v69, 0xffff0000, v202
	v_lshlrev_b32_e32 v68, 16, v202
	v_and_b32_e32 v75, 0xffff0000, v207
	v_lshlrev_b32_e32 v74, 16, v207
	v_and_b32_e32 v77, 0xffff0000, v206
	v_lshlrev_b32_e32 v76, 16, v206
	v_and_b32_e32 v83, 0xffff0000, v211
	v_lshlrev_b32_e32 v82, 16, v211
	v_and_b32_e32 v85, 0xffff0000, v210
	v_lshlrev_b32_e32 v84, 16, v210
	v_and_b32_e32 v91, 0xffff0000, v215
	v_lshlrev_b32_e32 v90, 16, v215
	v_and_b32_e32 v93, 0xffff0000, v214
	v_lshlrev_b32_e32 v92, 16, v214
	v_and_b32_e32 v115, 0xffff0000, v219
	v_lshlrev_b32_e32 v114, 16, v219
	v_and_b32_e32 v117, 0xffff0000, v218
	v_lshlrev_b32_e32 v116, 16, v218
	v_and_b32_e32 v119, 0xffff0000, v217
	v_lshlrev_b32_e32 v118, 16, v217
	v_and_b32_e32 v121, 0xffff0000, v216
	v_lshlrev_b32_e32 v120, 16, v216
	v_and_b32_e32 v123, 0xffff0000, v223
	v_lshlrev_b32_e32 v122, 16, v223
	v_and_b32_e32 v103, 0xffff0000, v222
	v_lshlrev_b32_e32 v102, 16, v222
	v_and_b32_e32 v107, 0xffff0000, v221
	v_lshlrev_b32_e32 v106, 16, v221
	v_and_b32_e32 v101, 0xffff0000, v220
	v_lshlrev_b32_e32 v100, 16, v220
	v_and_b32_e32 v105, 0xffff0000, v227
	v_lshlrev_b32_e32 v104, 16, v227
	v_and_b32_e32 v99, 0xffff0000, v226
	v_lshlrev_b32_e32 v98, 16, v226
	v_and_b32_e32 v111, 0xffff0000, v225
	v_lshlrev_b32_e32 v110, 16, v225
	v_pk_mul_f32 v[108:109], v[96:97], v[96:97]
	v_pk_fma_f32 v[108:109], v[110:111], v[110:111], v[108:109]
	v_and_b32_e32 v87, 0xffff0000, v209
	v_pk_fma_f32 v[108:109], v[98:99], v[98:99], v[108:109]
	v_pk_fma_f32 v[108:109], v[104:105], v[104:105], v[108:109]
	v_pk_fma_f32 v[108:109], v[100:101], v[100:101], v[108:109]
	v_pk_fma_f32 v[108:109], v[106:107], v[106:107], v[108:109]
	v_pk_fma_f32 v[108:109], v[102:103], v[102:103], v[108:109]
	v_pk_fma_f32 v[108:109], v[122:123], v[122:123], v[108:109]
	v_pk_fma_f32 v[108:109], v[120:121], v[120:121], v[108:109]
	v_pk_fma_f32 v[108:109], v[118:119], v[118:119], v[108:109]
	v_pk_fma_f32 v[108:109], v[116:117], v[116:117], v[108:109]
	v_pk_fma_f32 v[108:109], v[114:115], v[114:115], v[108:109]
	v_pk_fma_f32 v[108:109], v[112:113], v[112:113], v[108:109]
	v_pk_fma_f32 v[108:109], v[94:95], v[94:95], v[108:109]
	v_pk_fma_f32 v[108:109], v[92:93], v[92:93], v[108:109]
	v_pk_fma_f32 v[108:109], v[90:91], v[90:91], v[108:109]
	v_lshlrev_b32_e32 v86, 16, v209
	v_and_b32_e32 v89, 0xffff0000, v208
	v_lshlrev_b32_e32 v88, 16, v208
	v_pk_fma_f32 v[108:109], v[88:89], v[88:89], v[108:109]
	v_pk_fma_f32 v[108:109], v[86:87], v[86:87], v[108:109]
	v_pk_fma_f32 v[108:109], v[84:85], v[84:85], v[108:109]
	v_pk_fma_f32 v[108:109], v[82:83], v[82:83], v[108:109]
	v_and_b32_e32 v79, 0xffff0000, v205
	v_lshlrev_b32_e32 v78, 16, v205
	v_and_b32_e32 v81, 0xffff0000, v204
	v_lshlrev_b32_e32 v80, 16, v204
	v_pk_fma_f32 v[108:109], v[80:81], v[80:81], v[108:109]
	v_pk_fma_f32 v[108:109], v[78:79], v[78:79], v[108:109]
	v_pk_fma_f32 v[108:109], v[76:77], v[76:77], v[108:109]
	v_pk_fma_f32 v[108:109], v[74:75], v[74:75], v[108:109]
	v_and_b32_e32 v71, 0xffff0000, v201
	v_lshlrev_b32_e32 v70, 16, v201
	v_and_b32_e32 v73, 0xffff0000, v200
	v_lshlrev_b32_e32 v72, 16, v200
	v_pk_fma_f32 v[108:109], v[72:73], v[72:73], v[108:109]
	v_pk_fma_f32 v[108:109], v[70:71], v[70:71], v[108:109]
	v_pk_fma_f32 v[108:109], v[68:69], v[68:69], v[108:109]
	v_pk_fma_f32 v[108:109], v[66:67], v[66:67], v[108:109]
	v_and_b32_e32 v63, 0xffff0000, v197
	v_lshlrev_b32_e32 v62, 16, v197
	v_and_b32_e32 v65, 0xffff0000, v196
	v_lshlrev_b32_e32 v64, 16, v196
	v_pk_fma_f32 v[108:109], v[64:65], v[64:65], v[108:109]
	v_pk_fma_f32 v[108:109], v[62:63], v[62:63], v[108:109]
	v_pk_fma_f32 v[108:109], v[60:61], v[60:61], v[108:109]
	v_pk_fma_f32 v[108:109], v[58:59], v[58:59], v[108:109]
	v_add_f32_e32 v108, v108, v109
	v_mov_b32_e32 v0, v108
	s_nop 1
	v_permlane32_swap_b32_e32 v108, v0
	v_add_f32_e32 v0, v108, v0
	v_fmamk_f32 v0, v0, 0x3c000000, v233
	v_rsq_f32_e32 v0, v0
	s_nop 0
	v_pk_mul_f32 v[96:97], v[0:1], v[96:97] op_sel_hi:[0,1]
	s_waitcnt vmcnt(14)
; __device__ __forceinline__ unsigned pk2(float lo, float hi) { f32x2_t v = {lo, hi}; bf16x2_t b = __builtin_convertvector(v, bf16x2_t); return __builtin_bit_cast(unsigned, b); }
; __device__ __forceinline__ void cross_unit(lbyte* lds, bf16* CQ, const bf16* CKV, const float* gq, const float* gk, int layer, int b, int hc, int qblk0, int qstep, int nq) {
;     ...
;     for (int qi = 0; qi < nq; ++qi) { const int qblk = qblk0 + qi * qstep;
;     const size_t row = (size_t)b * SEQ + qblk * 256 + 32 * wid + l31;
;     bf16* qrow = CQ + row * 512 + hc * 128;
;     s16x8 qf[8];
; #pragma unroll
;     for (int c = 0; c < 8; ++c) qf[c] = *(const s16x8*)(qrow + 16 * c + 8 * h);
;     ...
; #pragma unroll
;       for (int c = 0; c < 8; ++c) { const f32x4 ga = *(const f32x4*)(gq + 16 * c + 8 * h), gb = *(const f32x4*)(gq + 16 * c + 8 * h + 4); u32x4 w;
;           w.x = pk2(bf2f((unsigned short)qf[c][0]) * rn * ga[0], bf2f((unsigned short)qf[c][1]) * rn * ga[1]); w.y = pk2(bf2f((unsigned short)qf[c][2]) * rn * ga[2], bf2f((unsigned short)qf[c][3]) * rn * ga[3]);
;           w.z = pk2(bf2f((unsigned short)qf[c][4]) * rn * gb[0], bf2f((unsigned short)qf[c][5]) * rn * gb[1]); w.w = pk2(bf2f((unsigned short)qf[c][6]) * rn * gb[2], bf2f((unsigned short)qf[c][7]) * rn * gb[3]);
;           qf[c] = __builtin_bit_cast(s16x8, w); } }
	v_pk_mul_f32 v[54:55], v[54:55], v[96:97]
	s_nop 0
	v_cvt_pk_bf16_f32 v96, v54, v55
	v_pk_mul_f32 v[54:55], v[0:1], v[110:111] op_sel_hi:[0,1]
	v_pk_mul_f32 v[54:55], v[56:57], v[54:55]
	s_nop 0
	v_cvt_pk_bf16_f32 v97, v54, v55
	v_pk_mul_f32 v[54:55], v[0:1], v[98:99] op_sel_hi:[0,1]
	v_pk_mul_f32 v[50:51], v[50:51], v[54:55]
	s_nop 0
	v_cvt_pk_bf16_f32 v98, v50, v51
	v_pk_mul_f32 v[50:51], v[0:1], v[104:105] op_sel_hi:[0,1]
	v_pk_mul_f32 v[50:51], v[52:53], v[50:51]
	s_nop 0
	v_cvt_pk_bf16_f32 v99, v50, v51
	v_pk_mul_f32 v[50:51], v[0:1], v[100:101] op_sel_hi:[0,1]
	s_waitcnt vmcnt(12)
	v_pk_mul_f32 v[46:47], v[46:47], v[50:51]
	s_nop 0
	v_cvt_pk_bf16_f32 v100, v46, v47
	v_pk_mul_f32 v[46:47], v[0:1], v[106:107] op_sel_hi:[0,1]
	v_pk_mul_f32 v[46:47], v[48:49], v[46:47]
	s_nop 0
	v_cvt_pk_bf16_f32 v101, v46, v47
	v_pk_mul_f32 v[46:47], v[0:1], v[102:103] op_sel_hi:[0,1]
	v_pk_mul_f32 v[42:43], v[42:43], v[46:47]
	s_nop 0
	v_cvt_pk_bf16_f32 v102, v42, v43
	v_pk_mul_f32 v[42:43], v[0:1], v[122:123] op_sel_hi:[0,1]
	v_pk_mul_f32 v[42:43], v[44:45], v[42:43]
	s_nop 0
	v_cvt_pk_bf16_f32 v103, v42, v43
	v_pk_mul_f32 v[42:43], v[0:1], v[120:121] op_sel_hi:[0,1]
	s_waitcnt vmcnt(10)
	v_pk_mul_f32 v[38:39], v[38:39], v[42:43]
	s_nop 0
	v_cvt_pk_bf16_f32 v104, v38, v39
	v_pk_mul_f32 v[38:39], v[0:1], v[118:119] op_sel_hi:[0,1]
	v_pk_mul_f32 v[38:39], v[40:41], v[38:39]
	s_nop 0
	v_cvt_pk_bf16_f32 v105, v38, v39
	v_pk_mul_f32 v[38:39], v[0:1], v[116:117] op_sel_hi:[0,1]
	v_pk_mul_f32 v[34:35], v[34:35], v[38:39]
	s_nop 0
	v_cvt_pk_bf16_f32 v106, v34, v35
	v_pk_mul_f32 v[34:35], v[0:1], v[114:115] op_sel_hi:[0,1]
	v_pk_mul_f32 v[34:35], v[36:37], v[34:35]
	s_nop 0
	v_cvt_pk_bf16_f32 v107, v34, v35
	v_pk_mul_f32 v[34:35], v[0:1], v[112:113] op_sel_hi:[0,1]
	s_waitcnt vmcnt(8)
	v_pk_mul_f32 v[30:31], v[34:35], v[30:31]
	s_nop 0
	v_cvt_pk_bf16_f32 v108, v30, v31
	v_pk_mul_f32 v[30:31], v[0:1], v[94:95] op_sel_hi:[0,1]
	v_pk_mul_f32 v[30:31], v[30:31], v[32:33]
	s_nop 0
	v_cvt_pk_bf16_f32 v109, v30, v31
	v_pk_mul_f32 v[30:31], v[0:1], v[92:93] op_sel_hi:[0,1]
	v_pk_mul_f32 v[26:27], v[30:31], v[26:27]
	s_nop 0
	v_cvt_pk_bf16_f32 v110, v26, v27
	v_pk_mul_f32 v[26:27], v[0:1], v[90:91] op_sel_hi:[0,1]
	v_pk_mul_f32 v[26:27], v[26:27], v[28:29]
	s_nop 0
	v_cvt_pk_bf16_f32 v111, v26, v27
	v_pk_mul_f32 v[26:27], v[0:1], v[88:89] op_sel_hi:[0,1]
	s_waitcnt vmcnt(6)
	v_pk_mul_f32 v[22:23], v[26:27], v[22:23]
	s_nop 0
	v_cvt_pk_bf16_f32 v112, v22, v23
	v_pk_mul_f32 v[22:23], v[0:1], v[86:87] op_sel_hi:[0,1]
	v_pk_mul_f32 v[22:23], v[22:23], v[24:25]
	s_nop 0
	v_cvt_pk_bf16_f32 v113, v22, v23
	v_pk_mul_f32 v[22:23], v[0:1], v[84:85] op_sel_hi:[0,1]
	v_pk_mul_f32 v[18:19], v[22:23], v[18:19]
	s_nop 0
	v_cvt_pk_bf16_f32 v114, v18, v19
	v_pk_mul_f32 v[18:19], v[0:1], v[82:83] op_sel_hi:[0,1]
	v_pk_mul_f32 v[18:19], v[18:19], v[20:21]
	s_nop 0
	v_cvt_pk_bf16_f32 v115, v18, v19
	v_pk_mul_f32 v[18:19], v[0:1], v[80:81] op_sel_hi:[0,1]
	s_waitcnt vmcnt(4)
	v_pk_mul_f32 v[14:15], v[18:19], v[14:15]
	s_nop 0
	v_cvt_pk_bf16_f32 v116, v14, v15
	v_pk_mul_f32 v[14:15], v[0:1], v[78:79] op_sel_hi:[0,1]
	v_pk_mul_f32 v[14:15], v[14:15], v[16:17]
	s_nop 0
	v_cvt_pk_bf16_f32 v117, v14, v15
	v_pk_mul_f32 v[14:15], v[0:1], v[76:77] op_sel_hi:[0,1]
	v_pk_mul_f32 v[10:11], v[14:15], v[10:11]
	v_mov_b32_e32 v14, v1
	v_cvt_pk_bf16_f32 v118, v10, v11
	v_pk_mul_f32 v[10:11], v[0:1], v[74:75] op_sel_hi:[0,1]
	v_pk_mul_f32 v[10:11], v[10:11], v[12:13]
	v_mov_b32_e32 v15, v1
	v_cvt_pk_bf16_f32 v119, v10, v11
	v_pk_mul_f32 v[10:11], v[0:1], v[72:73] op_sel_hi:[0,1]
	s_waitcnt vmcnt(2)
	v_pk_mul_f32 v[6:7], v[10:11], v[6:7]
	v_mov_b32_e32 v10, v1
	v_cvt_pk_bf16_f32 v120, v6, v7
	v_pk_mul_f32 v[6:7], v[0:1], v[70:71] op_sel_hi:[0,1]
	v_pk_mul_f32 v[6:7], v[6:7], v[8:9]
	v_mov_b32_e32 v8, v1
	v_cvt_pk_bf16_f32 v121, v6, v7
	v_pk_mul_f32 v[6:7], v[0:1], v[68:69] op_sel_hi:[0,1]
	v_pk_mul_f32 v[2:3], v[6:7], v[2:3]
	v_mov_b32_e32 v6, v1
	v_cvt_pk_bf16_f32 v122, v2, v3
	v_pk_mul_f32 v[2:3], v[0:1], v[66:67] op_sel_hi:[0,1]
	v_pk_mul_f32 v[2:3], v[2:3], v[4:5]
	v_mov_b32_e32 v4, v1
	v_cvt_pk_bf16_f32 v123, v2, v3
	v_pk_mul_f32 v[2:3], v[0:1], v[64:65] op_sel_hi:[0,1]
	s_waitcnt vmcnt(0)
	s_add_i32 s7, s0, 1
	v_readlane_b32 s6, v255, 7
	s_nop 0
	s_cmp_lt_u32 s7, s6
	s_cbranch_scc0 .Lcxq_nopf
	v_readlane_b32 s6, v254, 63
	s_nop 0
	s_mul_i32 s6, s7, s6
	s_add_i32 s6, s6, s68
	s_lshl_b32 s8, s6, 8
	s_ashr_i32 s9, s8, 31
	v_lshl_add_u64 v[228:229], v[148:149], 0, s[8:9]
	v_lshlrev_b64 v[228:229], 10, v[228:229]
	v_lshl_add_u64 v[228:229], v[152:153], 0, v[228:229]
	global_load_dwordx4 v[196:199], v[228:229], off offset:224
	global_load_dwordx4 v[200:203], v[228:229], off offset:192
	global_load_dwordx4 v[204:207], v[228:229], off offset:160
	global_load_dwordx4 v[208:211], v[228:229], off offset:128
	global_load_dwordx4 v[212:215], v[228:229], off offset:96
	global_load_dwordx4 v[216:219], v[228:229], off offset:64
	global_load_dwordx4 v[220:223], v[228:229], off offset:32
	global_load_dwordx4 v[224:227], v[228:229], off

; __device__ __forceinline__ float pair_max(float v) { auto r = __builtin_amdgcn_permlane32_swap(__float_as_uint(v), __float_as_uint(v), false, false); return fmaxf(__uint_as_float(r[0]), __uint_as_float(r[1])); }
; #define LDS_FENCE() asm volatile("" ::: "memory")
; template <int NS, int DT> __device__ __forceinline__ void softmax_upd(f32x16* s, float& m, float& l, f32x16* o) {
;     float mx = s[0][0];
; #pragma unroll
;     for (int i = 0; i < NS; ++i)
; #pragma unroll
;         for (int r = 0; r < 16; ++r) mx = fmaxf(mx, s[i][r]);
;     mx = pair_max(mx);
;     const bool grow = mx > m + 8.0f; const float mn = grow ? mx : m; float sum = 0.f;
;     if (__any(grow)) { const float alpha = __builtin_amdgcn_exp2f(m - mn); l *= alpha;
; #pragma unroll
;         for (int dt = 0; dt < DT; ++dt) o[dt] = o[dt] * alpha; }
; __device__ __forceinline__ void cross_unit(lbyte* lds, bf16* CQ, const bf16* CKV, const float* gq, const float* gk, int layer, int b, int hc, int qblk0, int qstep, int nq) {
;     ...
;     for (int t = 0; t < 8; ++t) {
;         f32x16 s[1]; s16x8 kf[8], vf[8];
;         load_k<8>(kf, lds + CX_K + (32 * t) * CX_KP, CX_KP, l31, h); load_v<4>(vf, lds + CX_V + 64 * t, CX_VP, l31, h); LDS_FENCE();
;         qk1<8>(s[0], kf, qf);
; #pragma unroll
;         for (int r = 0; r < 16; ++r) s[0][r] *= scale;
;         softmax_upd<1, 4>(s, m, l, o);
.LBB0_989:
	v_add_u32_e32 v0, 0, v159
	ds_read_b128 v[2:5], v0
	ds_read_b128 v[6:9], v0 offset:32
	v_add_u32_e32 v14, 0, v160
	v_add_u32_e32 v140, 0x15220, v14
	v_add_u32_e32 v141, 0x15230, v14
	s_waitcnt lgkmcnt(1)
	v_mfma_f32_32x32x16_bf16 v[80:95], v[2:5], v[96:99], 0
	ds_read_b128 v[2:5], v0 offset:64
	v_add_u32_e32 v142, 0x19400, v14
	v_add_u32_e32 v186, 0x1d620, v14
	v_add_u32_e32 v15, 0x11010, v14
	v_add_u32_e32 v161, 0x1d610, v14
	v_add_f32_e32 v163, 0x41000000, v162
	s_waitcnt lgkmcnt(1)
	v_mfma_f32_32x32x16_bf16 v[80:95], v[6:9], v[100:103], v[80:95]
	ds_read_b128 v[6:9], v0 offset:96
	s_waitcnt lgkmcnt(1)
	v_mfma_f32_32x32x16_bf16 v[80:95], v[2:5], v[104:107], v[80:95]
	ds_read_b128 v[2:5], v0 offset:128
	ds_read_b128 v[10:13], v0 offset:160
	ds_read_b128 v[132:135], v0 offset:192
	ds_read_b128 v[182:185], v0 offset:224
	v_add_u32_e32 v0, 0x11000, v14
	s_waitcnt lgkmcnt(4)
	v_mfma_f32_32x32x16_bf16 v[80:95], v[6:9], v[108:111], v[80:95]
	v_add_u32_e32 v6, 0x11020, v14
	v_add_u32_e32 v7, 0x11030, v14
	v_add_u32_e32 v8, 0x15200, v14
	v_add_u32_e32 v9, 0x15210, v14
	s_waitcnt lgkmcnt(3)
	v_mfma_f32_32x32x16_bf16 v[80:95], v[2:5], v[112:115], v[80:95]
	v_add_u32_e32 v2, 0x19410, v14
	v_add_u32_e32 v3, 0x19420, v14
	v_add_u32_e32 v4, 0x19430, v14
	v_add_u32_e32 v5, 0x1d600, v14
	v_add_u32_e32 v14, 0x1d630, v14
	s_waitcnt lgkmcnt(2)
	v_mfma_f32_32x32x16_bf16 v[80:95], v[10:13], v[116:119], v[80:95]
	ds_read_b64 v[136:137], v0
	ds_read_b64 v[138:139], v15
	ds_read_b64 v[128:129], v6
	ds_read_b64 v[130:131], v7
	ds_read_b64 v[144:145], v8
	ds_read_b64 v[146:147], v9
	ds_read_b64 v[10:11], v140
	ds_read_b64 v[12:13], v141
	s_waitcnt lgkmcnt(9)
	v_mfma_f32_32x32x16_bf16 v[80:95], v[132:135], v[120:123], v[80:95]
	ds_read_b64 v[140:141], v142
	ds_read_b64 v[142:143], v2
	ds_read_b64 v[6:7], v3
	ds_read_b64 v[8:9], v4
	ds_read_b64 v[132:133], v5
	ds_read_b64 v[134:135], v161
	ds_read_b64 v[2:3], v186
	ds_read_b64 v[4:5], v14
	s_waitcnt lgkmcnt(14)
	v_mfma_f32_32x32x16_bf16 v[80:95], v[182:185], v[124:127], v[80:95]
	s_nop 11
	v_mul_f32_e32 v187, s12, v80
	v_mul_f32_e32 v186, s12, v81
	v_mul_f32_e32 v185, s12, v82
	v_mul_f32_e32 v184, s12, v83
	v_max_f32_e32 v0, v187, v186
	v_mul_f32_e32 v183, s12, v84
	v_mul_f32_e32 v182, s12, v85
	v_max3_f32 v0, v0, v185, v184
	v_mul_f32_e32 v161, s12, v86
	v_mul_f32_e32 v86, s12, v87
	v_max3_f32 v0, v0, v183, v182
	v_mul_f32_e32 v85, s12, v88
	v_mul_f32_e32 v84, s12, v89
	v_max3_f32 v0, v0, v161, v86
	v_mul_f32_e32 v83, s12, v90
	v_mul_f32_e32 v82, s12, v91
	v_max3_f32 v0, v0, v85, v84
	v_mul_f32_e32 v81, s12, v92
	v_mul_f32_e32 v80, s12, v93
	v_max3_f32 v0, v0, v83, v82
	v_mul_f32_e32 v15, s12, v94
	v_mul_f32_e32 v14, s12, v95
	v_max3_f32 v0, v0, v81, v80
	v_max3_f32 v0, v0, v15, v14
	v_mov_b32_e32 v87, v0
	s_nop 1
	v_permlane32_swap_b32_e32 v0, v87
	v_max_f32_e32 v87, v87, v87
	v_max_f32_e32 v0, v0, v0
	v_max_f32_e32 v0, v0, v87
	v_cmp_gt_f32_e32 vcc, v0, v163
	s_nop 1
	v_cndmask_b32_e32 v0, v162, v0, vcc
	s_cbranch_vccz .LBB0_991
	v_sub_f32_e32 v87, v162, v0
	v_exp_f32_e32 v88, v87
	s_nop 0
	v_mul_f32_e32 v158, v158, v88
	v_pk_mul_f32 v[78:79], v[78:79], v[88:89] op_sel_hi:[1,0]
	v_pk_mul_f32 v[76:77], v[76:77], v[88:89] op_sel_hi:[1,0]
	v_pk_mul_f32 v[74:75], v[74:75], v[88:89] op_sel_hi:[1,0]
	v_pk_mul_f32 v[72:73], v[72:73], v[88:89] op_sel_hi:[1,0]
	v_pk_mul_f32 v[70:71], v[70:71], v[88:89] op_sel_hi:[1,0]
	v_pk_mul_f32 v[68:69], v[68:69], v[88:89] op_sel_hi:[1,0]
	v_pk_mul_f32 v[66:67], v[66:67], v[88:89] op_sel_hi:[1,0]
	v_pk_mul_f32 v[64:65], v[64:65], v[88:89] op_sel_hi:[1,0]
	v_pk_mul_f32 v[62:63], v[62:63], v[88:89] op_sel_hi:[1,0]
	v_pk_mul_f32 v[60:61], v[60:61], v[88:89] op_sel_hi:[1,0]
	v_pk_mul_f32 v[58:59], v[58:59], v[88:89] op_sel_hi:[1,0]
	v_pk_mul_f32 v[56:57], v[56:57], v[88:89] op_sel_hi:[1,0]
	v_pk_mul_f32 v[54:55], v[54:55], v[88:89] op_sel_hi:[1,0]
	v_pk_mul_f32 v[52:53], v[52:53], v[88:89] op_sel_hi:[1,0]
	v_pk_mul_f32 v[50:51], v[50:51], v[88:89] op_sel_hi:[1,0]
	v_pk_mul_f32 v[48:49], v[48:49], v[88:89] op_sel_hi:[1,0]
	v_pk_mul_f32 v[46:47], v[46:47], v[88:89] op_sel_hi:[1,0]
	v_pk_mul_f32 v[44:45], v[44:45], v[88:89] op_sel_hi:[1,0]
	v_pk_mul_f32 v[42:43], v[42:43], v[88:89] op_sel_hi:[1,0]
	v_pk_mul_f32 v[40:41], v[40:41], v[88:89] op_sel_hi:[1,0]
	v_pk_mul_f32 v[38:39], v[38:39], v[88:89] op_sel_hi:[1,0]
	v_pk_mul_f32 v[36:37], v[36:37], v[88:89] op_sel_hi:[1,0]
	v_pk_mul_f32 v[34:35], v[34:35], v[88:89] op_sel_hi:[1,0]
	v_pk_mul_f32 v[32:33], v[32:33], v[88:89] op_sel_hi:[1,0]
	v_pk_mul_f32 v[30:31], v[30:31], v[88:89] op_sel_hi:[1,0]
	v_pk_mul_f32 v[28:29], v[28:29], v[88:89] op_sel_hi:[1,0]
	v_pk_mul_f32 v[26:27], v[26:27], v[88:89] op_sel_hi:[1,0]
	v_pk_mul_f32 v[24:25], v[24:25], v[88:89] op_sel_hi:[1,0]
	v_pk_mul_f32 v[22:23], v[22:23], v[88:89] op_sel_hi:[1,0]
	v_pk_mul_f32 v[20:21], v[20:21], v[88:89] op_sel_hi:[1,0]
	v_pk_mul_f32 v[18:19], v[18:19], v[88:89] op_sel_hi:[1,0]
	v_pk_mul_f32 v[16:17], v[16:17], v[88:89] op_sel_hi:[1,0]
